# layer-0 w_in GEMM main tiles: XCDs 8 decode positions (one column tile) apart
# speedup vs baseline: 1.0068x; 1.0068x over previous
.Lgi_sk_rot0:
	s_and_b32 s0, s54, 7
	s_lshr_b32 s1, s54, 3
	s_mul_i32 s57, s0, 188
	s_add_u32 s1, s1, s57
	s_mul_i32 s57, s1, 0x5556
	s_lshr_b32 s57, s57, 22
	s_mul_i32 s57, s57, 192
	s_sub_u32 s1, s1, s57
	s_lshl_b32 s1, s1, 3
	s_or_b32 s57, s1, s0
	s_branch .Lgi_sk_dec
